# grid barrier: the globally-last workgroup publishes the new generation to every per-XCD word; followers poll their own XCD word (one hop, 64 pollers per address instead of 512 on one)
# baseline (speedup 1.0000x reference)
.LBB0_150:
	s_or_b64 exec, exec, s[40:41]
	s_and_saveexec_b64 s[40:41], s[42:43]
	s_cbranch_execz .LBB0_152
	global_atomic_add v[0:1], v223, off
	v_add_co_u32_e32 v2, vcc, 0xffffef00, v0
	s_nop 1
	v_addc_co_u32_e32 v3, vcc, -1, v1, vcc
	global_atomic_add v[2:3], v223, off
	global_atomic_add v[2:3], v223, off offset:256
	global_atomic_add v[2:3], v223, off offset:512
	global_atomic_add v[2:3], v223, off offset:768
	global_atomic_add v[2:3], v223, off offset:1024
	global_atomic_add v[2:3], v223, off offset:1280
	global_atomic_add v[2:3], v223, off offset:1536
	global_atomic_add v[2:3], v223, off offset:1792
	global_atomic_add v[2:3], v223, off offset:2048
	global_atomic_add v[2:3], v223, off offset:2304
	global_atomic_add v[2:3], v223, off offset:2560
	global_atomic_add v[2:3], v223, off offset:2816
	global_atomic_add v[2:3], v223, off offset:3072
	global_atomic_add v[2:3], v223, off offset:3328
	global_atomic_add v[2:3], v223, off offset:3584
	global_atomic_add v[2:3], v223, off offset:3840

.LBB0_471:
	s_or_b64 exec, exec, s[38:39]
	s_and_saveexec_b64 s[38:39], s[40:41]
	s_cbranch_execz .LBB0_473
	global_atomic_add v[0:1], v223, off
	v_add_co_u32_e32 v2, vcc, 0xffffef00, v0
	s_nop 1
	v_addc_co_u32_e32 v3, vcc, -1, v1, vcc
	global_atomic_add v[2:3], v223, off
	global_atomic_add v[2:3], v223, off offset:256
	global_atomic_add v[2:3], v223, off offset:512
	global_atomic_add v[2:3], v223, off offset:768
	global_atomic_add v[2:3], v223, off offset:1024
	global_atomic_add v[2:3], v223, off offset:1280
	global_atomic_add v[2:3], v223, off offset:1536
	global_atomic_add v[2:3], v223, off offset:1792
	global_atomic_add v[2:3], v223, off offset:2048
	global_atomic_add v[2:3], v223, off offset:2304
	global_atomic_add v[2:3], v223, off offset:2560
	global_atomic_add v[2:3], v223, off offset:2816
	global_atomic_add v[2:3], v223, off offset:3072
	global_atomic_add v[2:3], v223, off offset:3328
	global_atomic_add v[2:3], v223, off offset:3584
	global_atomic_add v[2:3], v223, off offset:3840
